# GEMM1 epilogue: per-tile bias and sum-of-squares vectors staged to LDS by two LDS-DMA loads issued in the last K iteration; epilogue reads them with ds_read instead of waiting on global loads
# speedup vs baseline: 1.0098x; 1.0098x over previous
.LBB0_269:
	s_cmp_eq_u32 s59, 12
	s_cselect_b64 s[40:41], -1, 0
	s_cmp_lg_u32 s59, 12
	s_cbranch_scc1 .LBB0_268
	s_lshl_b32 s98, s15, 2
	v_lshlrev_b32_e32 v252, 4, v233
	s_add_u32 s98, s86, s98
	s_addc_u32 s99, s87, 0
	s_add_i32 m0, s80, 0x20000
	s_lshl_b32 s100, s1, 2
	global_load_lds_dwordx4 v252, s[98:99]
	s_add_u32 s98, s44, s100
	s_addc_u32 s99, s45, 0
	s_add_i32 m0, s80, 0x22000
	s_nop 0
	global_load_lds_dwordx4 v252, s[98:99]
	s_branch .LBB0_268

.LBB0_273:
	s_mov_b64 s[22:23], -1
	s_and_b64 vcc, exec, s[16:17]
	s_cbranch_vccz .LBB0_340
	v_or_b32_e32 v70, s15, v205
	v_ashrrev_i32_e32 v71, 31, v70
	s_add_i32 s98, s80, 0x20000
	s_add_i32 s99, s80, 0x22000
	v_lshl_add_u32 v72, v205, 2, s98
	v_lshl_add_u32 v73, v193, 2, s99
	s_nop 0
	ds_read_b128 v[66:69], v72
	ds_read_b128 v[146:149], v72 offset:16
	ds_read_b128 v[50:53], v72 offset:528
	ds_read_b128 v[54:57], v72 offset:512
	ds_read_b32 v170, v73
	ds_read_b32 v168, v73 offset:64
	ds_read_b32 v166, v73 offset:128
	ds_read_b32 v164, v73 offset:192
	ds_read_b32 v182, v73 offset:512
	ds_read_b32 v180, v73 offset:576
	ds_read_b32 v178, v73 offset:640
	ds_read_b32 v72, v73 offset:704
	s_cmp_lg_u32 s21, 11
	s_cselect_b64 s[16:17], -1, 0
	s_cmp_eq_u32 s21, 11
	s_waitcnt lgkmcnt(0)
	v_fmamk_f32 v66, v66, 0x3a800000, v235
	v_fmamk_f32 v67, v67, 0x3a800000, v235
	v_fmamk_f32 v68, v68, 0x3a800000, v235
	v_fmamk_f32 v69, v69, 0x3a800000, v235
	v_fmamk_f32 v73, v146, 0x3a800000, v235
	v_fmamk_f32 v147, v147, 0x3a800000, v235
	v_fmamk_f32 v148, v148, 0x3a800000, v235
	v_fmamk_f32 v149, v149, 0x3a800000, v235
	v_rsq_f32_e32 v150, v66
	v_rsq_f32_e32 v151, v67
	v_rsq_f32_e32 v152, v68
	v_rsq_f32_e32 v153, v69
	v_rsq_f32_e32 v146, v73
	v_rsq_f32_e32 v148, v148
	v_rsq_f32_e32 v149, v149
	v_rsq_f32_e32 v147, v147
	v_pk_fma_f32 v[174:175], v[144:145], v[152:153], v[170:171] op_sel_hi:[1,1,0]
	v_pk_fma_f32 v[176:177], v[142:143], v[150:151], v[170:171] op_sel_hi:[1,1,0]
	v_pk_fma_f32 v[184:185], v[140:141], v[148:149], v[170:171] op_sel_hi:[1,1,0]
	v_pk_fma_f32 v[198:199], v[138:139], v[146:147], v[170:171] op_sel_hi:[1,1,0]
	s_cbranch_scc1 .LBB0_276
	v_cvt_pk_f16_f32 v66, v176, v177
	v_cvt_pk_f16_f32 v67, v174, v175
	v_cvt_pk_f16_f32 v68, v198, v199
	v_cvt_pk_f16_f32 v69, v184, v185
	s_mov_b64 s[22:23], 0

.LBB0_340:
	s_and_b64 vcc, exec, s[22:23]
	s_cbranch_vccz .LBB0_339
	s_lshl_b32 s1, s21, 1
	s_lshr_b32 s1, 0x11819, s1
	s_ashr_i32 s15, s14, 31
	s_and_b32 s16, s1, 3
	v_or_b32_e32 v174, s0, v205
	s_lshl_b64 s[0:1], s[14:15], 2
	s_add_u32 s0, s44, s0
	v_add_u32_e32 v176, 0x80, v172
	s_addc_u32 s1, s45, s1
	v_ashrrev_i32_e32 v175, 31, v174
	v_ashrrev_i32_e32 v177, 31, v176
	v_ashrrev_i32_e32 v173, 31, v172
	s_add_i32 s98, s80, 0x20000
	s_add_i32 s99, s80, 0x22000
	v_lshl_add_u32 v146, v193, 2, s98
	v_lshl_add_u32 v147, v205, 2, s99
	s_nop 0
	ds_read_b128 v[66:69], v147 offset:16
	ds_read_b128 v[70:73], v147
	ds_read_b32 v170, v146
	ds_read_b32 v168, v146 offset:64
	ds_read_b32 v166, v146 offset:128
	ds_read_b32 v164, v146 offset:192
	ds_read_b32 v171, v146 offset:512
	ds_read_b32 v169, v146 offset:576
	ds_read_b32 v167, v146 offset:640
	ds_read_b32 v165, v146 offset:704
	ds_read_b128 v[50:53], v147 offset:528
	ds_read_b128 v[54:57], v147 offset:512
	s_waitcnt lgkmcnt(0)
	v_fmamk_f32 v146, v170, 0x3a800000, v235
	v_rsq_f32_e32 v178, v146
	s_cmp_lt_i32 s16, 2
	s_mov_b64 s[14:15], -1
	v_pk_fma_f32 v[138:139], v[178:179], v[138:139], v[66:67] op_sel_hi:[0,1,1]
	v_pk_fma_f32 v[142:143], v[178:179], v[142:143], v[70:71] op_sel_hi:[0,1,1]
	v_pk_fma_f32 v[144:145], v[178:179], v[144:145], v[72:73] op_sel_hi:[0,1,1]
	v_pk_fma_f32 v[140:141], v[178:179], v[140:141], v[68:69] op_sel_hi:[0,1,1]
	s_cbranch_scc1 .LBB0_345
	v_mov_b64_e32 v[152:153], v[140:141]
	v_mov_b64_e32 v[148:149], v[144:145]
	s_cmp_eq_u32 s16, 2
	v_mov_b64_e32 v[150:151], v[138:139]
	v_mov_b64_e32 v[146:147], v[142:143]
	s_cbranch_scc0 .LBB0_344
	v_mul_f32_e32 v147, 0x3d372713, v138
	v_mul_f32_e32 v147, v138, v147
	v_mul_f32_e32 v148, 0x3d372713, v143
	v_fma_f32 v147, v138, v147, v138
	v_mul_f32_e32 v148, v143, v148
	v_mul_f32_e32 v147, 0x3fcc422a, v147
	v_fma_f32 v148, v143, v148, v143
	v_mul_f32_e32 v147, 0xbfb8aa3b, v147
	v_mul_f32_e32 v148, 0x3fcc422a, v148
	v_exp_f32_e32 v147, v147
	v_mul_f32_e32 v148, 0xbfb8aa3b, v148
	v_exp_f32_e32 v148, v148
	v_mul_f32_e32 v149, 0x3d372713, v144
	v_add_f32_e32 v147, 1.0, v147
	v_rcp_f32_e32 v150, v147
	v_add_f32_e32 v147, 1.0, v148
	v_mul_f32_e32 v148, 0x3d372713, v139
	v_mul_f32_e32 v151, 0x3d372713, v140
	v_mul_f32_e32 v148, v139, v148
	v_mul_f32_e32 v149, v144, v149
	v_mul_f32_e32 v151, v140, v151
	v_fma_f32 v148, v139, v148, v139
	v_fma_f32 v149, v144, v149, v144
	v_fma_f32 v151, v140, v151, v140
	v_mul_f32_e32 v148, 0x3fcc422a, v148
	v_mul_f32_e32 v149, 0x3fcc422a, v149
	v_mul_f32_e32 v151, 0x3fcc422a, v151
	v_mul_f32_e32 v148, 0xbfb8aa3b, v148
	v_mul_f32_e32 v149, 0xbfb8aa3b, v149
	v_mul_f32_e32 v151, 0xbfb8aa3b, v151
	v_exp_f32_e32 v148, v148
	v_exp_f32_e32 v149, v149
	v_exp_f32_e32 v151, v151
	v_mul_f32_e32 v146, 0x3d372713, v142
	v_add_f32_e32 v173, 1.0, v148
	v_add_f32_e32 v148, 1.0, v149
	v_add_f32_e32 v149, 1.0, v151
	v_mul_f32_e32 v151, 0x3d372713, v145
	v_mul_f32_e32 v152, 0x3d372713, v141
	v_mul_f32_e32 v146, v142, v146
	v_mul_f32_e32 v151, v145, v151
	v_mul_f32_e32 v152, v141, v152
	v_fma_f32 v146, v142, v146, v142
	v_fma_f32 v151, v145, v151, v145
	v_fma_f32 v152, v141, v152, v141
	v_mul_f32_e32 v146, 0x3fcc422a, v146
	v_mul_f32_e32 v151, 0x3fcc422a, v151
	v_mul_f32_e32 v152, 0x3fcc422a, v152
	v_mul_f32_e32 v146, 0xbfb8aa3b, v146
	v_mul_f32_e32 v151, 0xbfb8aa3b, v151
	v_mul_f32_e32 v152, 0xbfb8aa3b, v152
	v_exp_f32_e32 v146, v146
	v_exp_f32_e32 v151, v151
	v_exp_f32_e32 v153, v152
	v_rcp_f32_e32 v152, v149
	v_add_f32_e32 v146, 1.0, v146
	v_add_f32_e32 v149, 1.0, v151
	v_add_f32_e32 v151, 1.0, v153
	v_rcp_f32_e32 v146, v146
	v_rcp_f32_e32 v147, v147
	v_rcp_f32_e32 v148, v148
	v_rcp_f32_e32 v149, v149
	v_rcp_f32_e32 v153, v151
	v_rcp_f32_e32 v151, v173
	v_pk_mul_f32 v[146:147], v[142:143], v[146:147]
	v_pk_mul_f32 v[148:149], v[144:145], v[148:149]
	v_pk_mul_f32 v[152:153], v[140:141], v[152:153]
	v_pk_mul_f32 v[150:151], v[138:139], v[150:151]
